# attention epilogue: per-head RMS-norm row sums via DPP + permlane16_swap instead of serialized ds_bpermute chains
# speedup vs baseline: 1.0035x; 1.0008x over previous
; __device__ __forceinline__ void attn_unit(const bf16* __restrict__ P, bf16* __restrict__ MIXIN, const float* __restrict__ gn, int seq0, int h, int q0, int nt, float kmax0, float kmax1, float slope, float lam, char* lds) {
;     ...
;   if (mpe == 0) {
;     float g4[4];
; #pragma unroll
;     for (int d0 = 0; d0 < 4; ++d0) g4[d0] = gn[d0 * 32 + r32e] * 0.8f;
; #pragma unroll
;     for (int d0 = 0; d0 < 4; ++d0)
; #pragma unroll
;       for (int r = 0; r < 16; ++r) o[d0][r] = o[d0][r] * rli[r] - X[(wqe * 64 + d0 * 16 + r) * 64 + lanee];
;     bf16* Ow = MIXIN + (size_t)(seq0 + q0 + wqe * 32) * DM + h * 128 + r32e;
; #pragma unroll
;     for (int r = 0; r < 16; ++r) {
;       float ss = o[0][r] * o[0][r] + o[1][r] * o[1][r] + o[2][r] * o[2][r] + o[3][r] * o[3][r];
;       ss += __shfl_xor(ss, 1); ss += __shfl_xor(ss, 2); ss += __shfl_xor(ss, 4); ss += __shfl_xor(ss, 8); ss += __shfl_xor(ss, 16);
;       const float sc_ = 1.0f / sqrtf(ss * (1.0f / 128.0f) + EPS);
.LBB0_344:
	s_or_b64 exec, exec, s[0:1]
	v_cmp_gt_u32_e32 vcc, s28, v77
	s_waitcnt lgkmcnt(0)
	s_barrier
	s_and_saveexec_b64 s[6:7], vcc
	s_cbranch_execz .LBB0_291
	v_lshl_add_u32 v97, v68, 2, 0
	v_add_u32_e32 v98, v97, v69
	ds_read2st64_b32 v[68:69], v98 offset1:1
	v_lshlrev_b32_e32 v67, 2, v76
	global_load_dword v64, v67, s[8:9]
	global_load_dword v65, v67, s[8:9] offset:128
	global_load_dword v66, v67, s[8:9] offset:256
	s_waitcnt lgkmcnt(0)
	v_fma_f32 v75, v48, v94, -v68
	v_fma_f32 v74, v49, v96, -v69
	ds_read2st64_b32 v[48:49], v98 offset0:2 offset1:3
	global_load_dword v67, v67, s[8:9] offset:384
	s_add_i32 s0, s35, s31
	s_lshl_b32 s10, s24, 1
	s_waitcnt lgkmcnt(0)
	v_fma_f32 v73, v50, v92, -v48
	v_fma_f32 v72, v51, v93, -v49
	ds_read2st64_b32 v[48:49], v98 offset0:4 offset1:5
	s_waitcnt lgkmcnt(0)
	v_fma_f32 v71, v52, v89, -v48
	v_fma_f32 v70, v53, v91, -v49
	ds_read2st64_b32 v[48:49], v98 offset0:6 offset1:7
	s_waitcnt lgkmcnt(0)
	v_fma_f32 v69, v54, v80, -v48
	v_fma_f32 v68, v55, v81, -v49
	ds_read2st64_b32 v[48:49], v98 offset0:8 offset1:9
	s_waitcnt lgkmcnt(0)
	v_fma_f32 v55, v56, v87, -v48
	v_fma_f32 v54, v57, v88, -v49
	ds_read2st64_b32 v[48:49], v98 offset0:10 offset1:11
	ds_read2st64_b32 v[56:57], v98 offset0:14 offset1:15
	s_waitcnt lgkmcnt(1)
	v_fma_f32 v53, v58, v85, -v48
	v_fma_f32 v52, v59, v86, -v49
	ds_read2st64_b32 v[48:49], v98 offset0:12 offset1:13
	s_waitcnt lgkmcnt(0)
	v_fma_f32 v51, v60, v83, -v48
	v_fma_f32 v50, v61, v84, -v49
	v_fma_f32 v49, v62, v82, -v56
	v_fma_f32 v48, v63, v79, -v57
	ds_read2st64_b32 v[56:57], v98 offset0:16 offset1:17
	s_waitcnt lgkmcnt(0)
	v_fma_f32 v63, v32, v94, -v56
	v_fma_f32 v62, v33, v96, -v57
	ds_read2st64_b32 v[32:33], v98 offset0:18 offset1:19
	s_waitcnt lgkmcnt(0)
	v_fma_f32 v61, v34, v92, -v32
	v_fma_f32 v60, v35, v93, -v33
	ds_read2st64_b32 v[32:33], v98 offset0:20 offset1:21
	s_waitcnt lgkmcnt(0)
	v_fma_f32 v59, v36, v89, -v32
	v_fma_f32 v58, v37, v91, -v33
	ds_read2st64_b32 v[32:33], v98 offset0:22 offset1:23
	s_waitcnt lgkmcnt(0)
	v_fma_f32 v57, v38, v80, -v32
	v_fma_f32 v56, v39, v81, -v33
	ds_read2st64_b32 v[32:33], v98 offset0:24 offset1:25
	s_waitcnt vmcnt(3)
	v_mul_f32_e32 v64, 0x3f4ccccd, v64
	s_waitcnt vmcnt(2)
	v_mul_f32_e32 v65, 0x3f4ccccd, v65
	s_waitcnt lgkmcnt(0)
	v_fma_f32 v39, v40, v87, -v32
	v_fma_f32 v38, v41, v88, -v33
	ds_read2st64_b32 v[32:33], v98 offset0:26 offset1:27
	ds_read2st64_b32 v[40:41], v98 offset0:30 offset1:31
	s_waitcnt vmcnt(1)
	v_mul_f32_e32 v66, 0x3f4ccccd, v66
	s_waitcnt vmcnt(0)
	v_mul_f32_e32 v67, 0x3f4ccccd, v67
	s_waitcnt lgkmcnt(1)
	v_fma_f32 v37, v42, v85, -v32
	v_fma_f32 v36, v43, v86, -v33
	ds_read2st64_b32 v[32:33], v98 offset0:28 offset1:29
	s_waitcnt lgkmcnt(0)
	v_fma_f32 v35, v44, v83, -v32
	v_fma_f32 v34, v45, v84, -v33
	v_fma_f32 v33, v46, v82, -v40
	v_fma_f32 v32, v47, v79, -v41
	ds_read2st64_b32 v[40:41], v98 offset0:32 offset1:33
	s_waitcnt lgkmcnt(0)
	v_fma_f32 v95, v16, v94, -v40
	v_fma_f32 v46, v17, v96, -v41
	ds_read2st64_b32 v[16:17], v98 offset0:34 offset1:35
	s_waitcnt lgkmcnt(0)
	v_fma_f32 v45, v18, v92, -v16
	v_fma_f32 v44, v19, v93, -v17
	ds_read2st64_b32 v[16:17], v98 offset0:36 offset1:37
	s_waitcnt lgkmcnt(0)
	v_fma_f32 v43, v20, v89, -v16
	v_fma_f32 v42, v21, v91, -v17
	ds_read2st64_b32 v[16:17], v98 offset0:38 offset1:39
	s_waitcnt lgkmcnt(0)
	v_fma_f32 v41, v22, v80, -v16
	v_fma_f32 v40, v23, v81, -v17
	ds_read2st64_b32 v[16:17], v98 offset0:40 offset1:41
	s_waitcnt lgkmcnt(0)
	v_fma_f32 v24, v24, v87, -v16
	v_fma_f32 v23, v25, v88, -v17
	ds_read2st64_b32 v[16:17], v98 offset0:42 offset1:43
	s_waitcnt lgkmcnt(0)
	v_fma_f32 v21, v26, v85, -v16
	v_fma_f32 v20, v27, v86, -v17
	ds_read2st64_b32 v[16:17], v98 offset0:44 offset1:45
	ds_read2st64_b32 v[26:27], v98 offset0:46 offset1:47
	s_waitcnt lgkmcnt(1)
	v_fma_f32 v19, v28, v83, -v16
	v_fma_f32 v18, v29, v84, -v17
	s_waitcnt lgkmcnt(0)
	v_fma_f32 v17, v30, v82, -v26
	v_fma_f32 v16, v31, v79, -v27
	ds_read2st64_b32 v[26:27], v98 offset0:48 offset1:49
	s_waitcnt lgkmcnt(0)
	v_fma_f32 v99, v0, v94, -v26
	v_fma_f32 v94, v1, v96, -v27
	ds_read2st64_b32 v[0:1], v98 offset0:50 offset1:51
	s_waitcnt lgkmcnt(0)
	v_fma_f32 v47, v2, v92, -v0
	v_mul_f32_e32 v2, v63, v63
	v_fmac_f32_e32 v2, v75, v75
	v_fmac_f32_e32 v2, v95, v95
	v_fmac_f32_e32 v2, v99, v99
	v_fma_f32 v31, v3, v93, -v1
	ds_read2st64_b32 v[0:1], v98 offset0:52 offset1:53
	ds_bpermute_b32 v3, v228, v2
	s_waitcnt lgkmcnt(1)
	v_fma_f32 v30, v4, v89, -v0
	v_fma_f32 v29, v5, v91, -v1
	ds_read2st64_b32 v[0:1], v98 offset0:54 offset1:55
	s_waitcnt lgkmcnt(1)
	v_add_f32_e32 v2, v2, v3
	ds_bpermute_b32 v3, v227, v2
	s_waitcnt lgkmcnt(1)
	v_fma_f32 v28, v6, v80, -v0
	v_fma_f32 v27, v7, v81, -v1
	ds_read2st64_b32 v[0:1], v98 offset0:56 offset1:57
	s_waitcnt lgkmcnt(1)
	v_add_f32_e32 v2, v2, v3
	ds_bpermute_b32 v3, v226, v2
	s_waitcnt lgkmcnt(1)
	v_fma_f32 v26, v8, v87, -v0
	v_fma_f32 v25, v9, v88, -v1
	ds_read2st64_b32 v[0:1], v98 offset0:58 offset1:59
	s_waitcnt lgkmcnt(1)
	v_add_f32_e32 v2, v2, v3
	ds_bpermute_b32 v3, v225, v2
	s_waitcnt lgkmcnt(1)
	v_fma_f32 v22, v10, v85, -v0
	v_fma_f32 v10, v11, v86, -v1
	ds_read2st64_b32 v[0:1], v98 offset0:60 offset1:61
	s_waitcnt lgkmcnt(1)
	v_add_f32_e32 v2, v2, v3
	ds_bpermute_b32 v3, v224, v2
	s_waitcnt lgkmcnt(1)
	v_fma_f32 v9, v12, v83, -v0
	ds_read_b32 v0, v98 offset:15872
	s_waitcnt lgkmcnt(1)
	v_add_f32_e32 v2, v2, v3
	v_fmamk_f32 v2, v2, 0x3c000000, v221
	v_cmp_gt_f32_e32 vcc, s26, v2
	v_mul_f32_e32 v3, 0x4f800000, v2
	s_waitcnt lgkmcnt(0)
	v_fma_f32 v7, v14, v82, -v0
	v_or_b32_e32 v0, 0x3f00, v90
	v_add_u32_e32 v0, v97, v0
	ds_read_b32 v0, v0
	v_cndmask_b32_e32 v2, v2, v3, vcc
	v_sqrt_f32_e32 v3, v2
	v_fma_f32 v8, v13, v84, -v1
	s_waitcnt lgkmcnt(0)
; __device__ __forceinline__ unsigned f2bf(float f) { unsigned u = __builtin_bit_cast(unsigned, f); return (u + 0x7fffu + ((u >> 16) & 1u)) >> 16; }
; __device__ __forceinline__ int crow(int r, int hi) { return (r & 3) + 8 * (r >> 2) + 4 * hi; }
; __device__ __forceinline__ void attn_unit(const bf16* __restrict__ P, bf16* __restrict__ MIXIN, const float* __restrict__ gn, int seq0, int h, int q0, int nt, float kmax0, float kmax1, float slope, float lam, char* lds) {
;     ...
;     for (int r = 0; r < 16; ++r) {
;       float ss = o[0][r] * o[0][r] + o[1][r] * o[1][r] + o[2][r] * o[2][r] + o[3][r] * o[3][r];
;       ss += __shfl_xor(ss, 1); ss += __shfl_xor(ss, 2); ss += __shfl_xor(ss, 4); ss += __shfl_xor(ss, 8); ss += __shfl_xor(ss, 16);
;       const float sc_ = 1.0f / sqrtf(ss * (1.0f / 128.0f) + EPS);
;       const int orow = crow(r, hie);
; #pragma unroll
;       for (int d0 = 0; d0 < 4; ++d0) Ow[(size_t)orow * DM + d0 * 32] = (bf16)f2bf(o[d0][r] * sc_ * g4[d0]);
	v_fma_f32 v6, v15, v79, -v0
	v_lshlrev_b32_e32 v0, 10, v77
	v_add_u32_e32 v4, -1, v3
	v_and_b32_e32 v0, 0x30000, v0
	v_fma_f32 v5, -v4, v3, v2
	v_lshl_or_b32 v176, s0, 11, v0
	v_cmp_ge_f32_e64 s[0:1], 0, v5
	v_add_u32_e32 v5, 1, v3
	v_lshl_add_u64 v[0:1], s[46:47], 0, v[176:177]
	v_cndmask_b32_e64 v4, v3, v4, s[0:1]
	v_fma_f32 v3, -v5, v3, v2
	v_cmp_lt_f32_e64 s[0:1], 0, v3
	v_lshl_add_u64 v[0:1], v[0:1], 0, s[10:11]
	v_lshlrev_b32_e32 v176, 1, v76
	v_cndmask_b32_e64 v3, v4, v5, s[0:1]
	v_mul_f32_e32 v4, 0x37800000, v3
	v_cndmask_b32_e32 v3, v3, v4, vcc
	v_cmp_class_f32_e32 vcc, v2, v220
	v_lshl_add_u64 v[0:1], v[0:1], 0, v[176:177]
	v_lshlrev_b32_e32 v176, 13, v78
	v_cndmask_b32_e32 v2, v3, v2, vcc
	v_div_scale_f32 v3, s[0:1], v2, v2, 1.0
	v_rcp_f32_e32 v4, v3
	v_lshl_add_u64 v[0:1], v[0:1], 0, v[176:177]
	v_fma_f32 v5, -v3, v4, 1.0
	v_fmac_f32_e32 v4, v5, v4
	v_div_scale_f32 v5, vcc, 1.0, v2, 1.0
	v_mul_f32_e32 v11, v5, v4
	v_fma_f32 v12, -v3, v11, v5
	v_fmac_f32_e32 v11, v12, v4
	v_fma_f32 v3, -v3, v11, v5
	v_div_fmas_f32 v3, v3, v4, v11
	v_div_fixup_f32 v2, v3, v2, 1.0
	v_mul_f32_e32 v3, v75, v2
	v_mul_f32_e32 v3, v64, v3
	v_bfe_u32 v4, v3, 16, 1
	v_add3_u32 v3, v3, v4, s30
	global_store_short_d16_hi v[0:1], v3, off
	v_mul_f32_e32 v3, v63, v2
	v_mul_f32_e32 v3, v65, v3
	v_bfe_u32 v4, v3, 16, 1
	v_add3_u32 v3, v3, v4, s30
	global_store_short_d16_hi v[0:1], v3, off offset:64
	v_mul_f32_e32 v3, v95, v2
	v_mul_f32_e32 v3, v66, v3
	v_bfe_u32 v4, v3, 16, 1
	v_mul_f32_e32 v2, v99, v2
	v_add3_u32 v3, v3, v4, s30
	v_mul_f32_e32 v2, v67, v2
	global_store_short_d16_hi v[0:1], v3, off offset:128
	v_bfe_u32 v3, v2, 16, 1
	v_add3_u32 v2, v2, v3, s30
	global_store_short_d16_hi v[0:1], v2, off offset:192
	v_mul_f32_e32 v2, v62, v62
	v_fmac_f32_e32 v2, v74, v74
	v_fmac_f32_e32 v2, v46, v46
	v_fmac_f32_e32 v2, v94, v94
	s_nop 1
	s_waitcnt lgkmcnt(0)
	v_add_f32_dpp v2, v2, v2 quad_perm:[1,0,3,2] row_mask:0xf bank_mask:0xf
	s_nop 1
	s_waitcnt lgkmcnt(0)
	v_add_f32_dpp v2, v2, v2 quad_perm:[2,3,0,1] row_mask:0xf bank_mask:0xf
	s_nop 1
	s_waitcnt lgkmcnt(0)
	v_add_f32_dpp v2, v2, v2 row_half_mirror row_mask:0xf bank_mask:0xf
	s_nop 1
	s_waitcnt lgkmcnt(0)
	v_add_f32_dpp v2, v2, v2 row_mirror row_mask:0xf bank_mask:0xf
	v_mov_b32_e32 v3, v2
	s_waitcnt lgkmcnt(0)
	s_nop 0
	v_permlane16_swap_b32_e32 v2, v3
	v_add_f32_e32 v2, v2, v3
	v_fmamk_f32 v2, v2, 0x3c000000, v221
	v_cmp_gt_f32_e32 vcc, s26, v2
	v_mul_f32_e32 v3, 0x4f800000, v2
	s_nop 0
	v_cndmask_b32_e32 v2, v2, v3, vcc
	v_sqrt_f32_e32 v3, v2
	s_nop 0
	v_add_u32_e32 v4, -1, v3
	v_fma_f32 v5, -v4, v3, v2
	v_cmp_ge_f32_e64 s[0:1], 0, v5
	v_add_u32_e32 v5, 1, v3
	s_nop 0
	v_cndmask_b32_e64 v4, v3, v4, s[0:1]
	v_fma_f32 v3, -v5, v3, v2
	v_cmp_lt_f32_e64 s[0:1], 0, v3
	s_nop 1
	v_cndmask_b32_e64 v3, v4, v5, s[0:1]
	v_mul_f32_e32 v4, 0x37800000, v3
	v_cndmask_b32_e32 v3, v3, v4, vcc
	v_cmp_class_f32_e32 vcc, v2, v220
	s_nop 1
	v_cndmask_b32_e32 v2, v3, v2, vcc
	v_div_scale_f32 v3, s[0:1], v2, v2, 1.0
	v_rcp_f32_e32 v4, v3
	s_nop 0
	v_fma_f32 v5, -v3, v4, 1.0
	v_fmac_f32_e32 v4, v5, v4
	v_div_scale_f32 v5, vcc, 1.0, v2, 1.0
	v_mul_f32_e32 v11, v5, v4
	v_fma_f32 v12, -v3, v11, v5
	v_fmac_f32_e32 v11, v12, v4
	v_fma_f32 v3, -v3, v11, v5
	v_div_fmas_f32 v3, v3, v4, v11
	v_div_fixup_f32 v2, v3, v2, 1.0
	v_mul_f32_e32 v3, v74, v2
	v_mul_f32_e32 v3, v64, v3
	v_bfe_u32 v4, v3, 16, 1
	v_add3_u32 v3, v3, v4, s30
	global_store_short_d16_hi v[0:1], v3, off offset:2048
	v_mul_f32_e32 v3, v62, v2
	v_mul_f32_e32 v3, v65, v3
	v_bfe_u32 v4, v3, 16, 1
	v_add3_u32 v3, v3, v4, s30
	global_store_short_d16_hi v[0:1], v3, off offset:2112
	v_mul_f32_e32 v3, v46, v2
	v_mul_f32_e32 v3, v66, v3
	v_bfe_u32 v4, v3, 16, 1
	v_mul_f32_e32 v2, v94, v2
	v_add3_u32 v3, v3, v4, s30
	v_mul_f32_e32 v2, v67, v2
	global_store_short_d16_hi v[0:1], v3, off offset:2176
	v_bfe_u32 v3, v2, 16, 1
	v_add3_u32 v2, v2, v3, s30
	global_store_short_d16_hi v[0:1], v2, off offset:2240
	v_mul_f32_e32 v2, v61, v61
	v_fmac_f32_e32 v2, v73, v73
	v_fmac_f32_e32 v2, v45, v45
	v_fmac_f32_e32 v2, v47, v47
	s_nop 1
	s_waitcnt lgkmcnt(0)
	v_add_f32_dpp v2, v2, v2 quad_perm:[1,0,3,2] row_mask:0xf bank_mask:0xf
	s_nop 1
	s_waitcnt lgkmcnt(0)
	v_add_f32_dpp v2, v2, v2 quad_perm:[2,3,0,1] row_mask:0xf bank_mask:0xf
	s_nop 1
	s_waitcnt lgkmcnt(0)
	v_add_f32_dpp v2, v2, v2 row_half_mirror row_mask:0xf bank_mask:0xf
	s_nop 1
	s_waitcnt lgkmcnt(0)
	v_add_f32_dpp v2, v2, v2 row_mirror row_mask:0xf bank_mask:0xf
	v_mov_b32_e32 v3, v2
	s_waitcnt lgkmcnt(0)
	s_nop 0
	v_permlane16_swap_b32_e32 v2, v3
	v_add_f32_e32 v2, v2, v3
	v_fmamk_f32 v2, v2, 0x3c000000, v221
	v_cmp_gt_f32_e32 vcc, s26, v2
	v_mul_f32_e32 v3, 0x4f800000, v2
	s_nop 0
	v_cndmask_b32_e32 v2, v2, v3, vcc
	v_sqrt_f32_e32 v3, v2
	s_nop 0
	v_add_u32_e32 v4, -1, v3
	v_fma_f32 v5, -v4, v3, v2
	v_cmp_ge_f32_e64 s[0:1], 0, v5
	v_add_u32_e32 v5, 1, v3
	s_nop 0
	v_cndmask_b32_e64 v4, v3, v4, s[0:1]
	v_fma_f32 v3, -v5, v3, v2
	v_cmp_lt_f32_e64 s[0:1], 0, v3
	s_nop 1
	v_cndmask_b32_e64 v3, v4, v5, s[0:1]
	v_mul_f32_e32 v4, 0x37800000, v3
	v_cndmask_b32_e32 v3, v3, v4, vcc
	v_cmp_class_f32_e32 vcc, v2, v220
	s_nop 1
	v_cndmask_b32_e32 v2, v3, v2, vcc
	v_div_scale_f32 v3, s[0:1], v2, v2, 1.0
	v_rcp_f32_e32 v4, v3
	s_movk_i32 s0, 0x1000
	v_fma_f32 v5, -v3, v4, 1.0
	v_fmac_f32_e32 v4, v5, v4
	v_div_scale_f32 v5, vcc, 1.0, v2, 1.0
	v_mul_f32_e32 v11, v5, v4
	v_fma_f32 v12, -v3, v11, v5
	v_fmac_f32_e32 v11, v12, v4
	v_fma_f32 v3, -v3, v11, v5
	v_div_fmas_f32 v3, v3, v4, v11
	v_div_fixup_f32 v4, v3, v2, 1.0
	v_mul_f32_e32 v2, v73, v4
	v_mul_f32_e32 v2, v64, v2
	v_bfe_u32 v3, v2, 16, 1
	v_add3_u32 v5, v2, v3, s30
	v_add_co_u32_e32 v2, vcc, s0, v0
	s_nop 1
	v_addc_co_u32_e32 v3, vcc, 0, v1, vcc
	global_store_short_d16_hi v[2:3], v5, off
	v_mul_f32_e32 v5, v61, v4
	v_mul_f32_e32 v5, v65, v5
	v_bfe_u32 v11, v5, 16, 1
	v_add3_u32 v5, v5, v11, s30
	global_store_short_d16_hi v[2:3], v5, off offset:64
	v_mul_f32_e32 v5, v45, v4
	v_mul_f32_e32 v5, v66, v5
	v_bfe_u32 v11, v5, 16, 1
	v_mul_f32_e32 v4, v47, v4
	v_add3_u32 v5, v5, v11, s30
	v_mul_f32_e32 v4, v67, v4
	global_store_short_d16_hi v[2:3], v5, off offset:128
	v_bfe_u32 v5, v4, 16, 1
	v_add3_u32 v4, v4, v5, s30
	global_store_short_d16_hi v[2:3], v4, off offset:192
	v_mul_f32_e32 v4, v60, v60
	v_fmac_f32_e32 v4, v72, v72
	v_fmac_f32_e32 v4, v44, v44
	v_fmac_f32_e32 v4, v31, v31
	s_nop 1
	s_waitcnt lgkmcnt(0)
; __device__ __forceinline__ unsigned f2bf(float f) { unsigned u = __builtin_bit_cast(unsigned, f); return (u + 0x7fffu + ((u >> 16) & 1u)) >> 16; }
; __device__ __forceinline__ int crow(int r, int hi) { return (r & 3) + 8 * (r >> 2) + 4 * hi; }
; __device__ __forceinline__ void attn_unit(const bf16* __restrict__ P, bf16* __restrict__ MIXIN, const float* __restrict__ gn, int seq0, int h, int q0, int nt, float kmax0, float kmax1, float slope, float lam, char* lds) {
;     ...
;     for (int r = 0; r < 16; ++r) {
;       float ss = o[0][r] * o[0][r] + o[1][r] * o[1][r] + o[2][r] * o[2][r] + o[3][r] * o[3][r];
;       ss += __shfl_xor(ss, 1); ss += __shfl_xor(ss, 2); ss += __shfl_xor(ss, 4); ss += __shfl_xor(ss, 8); ss += __shfl_xor(ss, 16);
;       const float sc_ = 1.0f / sqrtf(ss * (1.0f / 128.0f) + EPS);
;       const int orow = crow(r, hie);
; #pragma unroll
;       for (int d0 = 0; d0 < 4; ++d0) Ow[(size_t)orow * DM + d0 * 32] = (bf16)f2bf(o[d0][r] * sc_ * g4[d0]);
	v_add_f32_dpp v4, v4, v4 quad_perm:[1,0,3,2] row_mask:0xf bank_mask:0xf
	s_nop 1
	s_waitcnt lgkmcnt(0)
	v_add_f32_dpp v4, v4, v4 quad_perm:[2,3,0,1] row_mask:0xf bank_mask:0xf
	s_nop 1
	s_waitcnt lgkmcnt(0)
	v_add_f32_dpp v4, v4, v4 row_half_mirror row_mask:0xf bank_mask:0xf
	s_nop 1
	s_waitcnt lgkmcnt(0)
	v_add_f32_dpp v4, v4, v4 row_mirror row_mask:0xf bank_mask:0xf
	v_mov_b32_e32 v5, v4
	s_waitcnt lgkmcnt(0)
	s_nop 0
	v_permlane16_swap_b32_e32 v4, v5
	v_add_f32_e32 v4, v4, v5
	v_fmamk_f32 v4, v4, 0x3c000000, v221
	v_cmp_gt_f32_e32 vcc, s26, v4
	v_mul_f32_e32 v5, 0x4f800000, v4
	s_nop 0
	v_cndmask_b32_e32 v4, v4, v5, vcc
	v_sqrt_f32_e32 v5, v4
	s_nop 0
	v_add_u32_e32 v11, -1, v5
	v_fma_f32 v12, -v11, v5, v4
	v_cmp_ge_f32_e64 s[0:1], 0, v12
	v_add_u32_e32 v12, 1, v5
	s_nop 0
	v_cndmask_b32_e64 v11, v5, v11, s[0:1]
	v_fma_f32 v5, -v12, v5, v4
	v_cmp_lt_f32_e64 s[0:1], 0, v5
	s_nop 1
	v_cndmask_b32_e64 v5, v11, v12, s[0:1]
	v_mul_f32_e32 v11, 0x37800000, v5
	v_cndmask_b32_e32 v5, v5, v11, vcc
	v_cmp_class_f32_e32 vcc, v4, v220
	s_nop 1
	v_cndmask_b32_e32 v4, v5, v4, vcc
	v_div_scale_f32 v5, s[0:1], v4, v4, 1.0
	v_rcp_f32_e32 v11, v5
	s_nop 0
	v_fma_f32 v12, -v5, v11, 1.0
	v_fmac_f32_e32 v11, v12, v11
	v_div_scale_f32 v12, vcc, 1.0, v4, 1.0
	v_mul_f32_e32 v13, v12, v11
	v_fma_f32 v14, -v5, v13, v12
	v_fmac_f32_e32 v13, v14, v11
	v_fma_f32 v5, -v5, v13, v12
	v_div_fmas_f32 v5, v5, v11, v13
	v_div_fixup_f32 v4, v5, v4, 1.0
	v_mul_f32_e32 v5, v72, v4
	v_mul_f32_e32 v5, v64, v5
	v_bfe_u32 v11, v5, 16, 1
	v_add3_u32 v5, v5, v11, s30
	global_store_short_d16_hi v[2:3], v5, off offset:2048
	v_mul_f32_e32 v5, v60, v4
	v_mul_f32_e32 v5, v65, v5
	v_bfe_u32 v11, v5, 16, 1
	v_add3_u32 v5, v5, v11, s30
	global_store_short_d16_hi v[2:3], v5, off offset:2112
	v_mul_f32_e32 v5, v44, v4
	v_mul_f32_e32 v5, v66, v5
	v_bfe_u32 v11, v5, 16, 1
	v_mul_f32_e32 v4, v31, v4
	v_add3_u32 v5, v5, v11, s30
	v_mul_f32_e32 v4, v67, v4
	global_store_short_d16_hi v[2:3], v5, off offset:2176
	v_bfe_u32 v5, v4, 16, 1
	v_add3_u32 v4, v4, v5, s30
	global_store_short_d16_hi v[2:3], v4, off offset:2240
	v_mul_f32_e32 v2, v59, v59
	v_fmac_f32_e32 v2, v71, v71
	v_fmac_f32_e32 v2, v43, v43
	v_fmac_f32_e32 v2, v30, v30
	s_nop 1
	s_waitcnt lgkmcnt(0)
	v_add_f32_dpp v2, v2, v2 quad_perm:[1,0,3,2] row_mask:0xf bank_mask:0xf
	s_nop 1
	s_waitcnt lgkmcnt(0)
	v_add_f32_dpp v2, v2, v2 quad_perm:[2,3,0,1] row_mask:0xf bank_mask:0xf
	s_nop 1
	s_waitcnt lgkmcnt(0)
	v_add_f32_dpp v2, v2, v2 row_half_mirror row_mask:0xf bank_mask:0xf
	s_nop 1
	s_waitcnt lgkmcnt(0)
	v_add_f32_dpp v2, v2, v2 row_mirror row_mask:0xf bank_mask:0xf
	v_mov_b32_e32 v3, v2
	s_waitcnt lgkmcnt(0)
	s_nop 0
	v_permlane16_swap_b32_e32 v2, v3
	v_add_f32_e32 v2, v2, v3
	v_fmamk_f32 v2, v2, 0x3c000000, v221
	v_cmp_gt_f32_e32 vcc, s26, v2
	v_mul_f32_e32 v3, 0x4f800000, v2
	s_nop 0
	v_cndmask_b32_e32 v2, v2, v3, vcc
	v_sqrt_f32_e32 v3, v2
	s_nop 0
	v_add_u32_e32 v4, -1, v3
	v_fma_f32 v5, -v4, v3, v2
	v_cmp_ge_f32_e64 s[0:1], 0, v5
	v_add_u32_e32 v5, 1, v3
	s_nop 0
	v_cndmask_b32_e64 v4, v3, v4, s[0:1]
	v_fma_f32 v3, -v5, v3, v2
	v_cmp_lt_f32_e64 s[0:1], 0, v3
	s_nop 1
	v_cndmask_b32_e64 v3, v4, v5, s[0:1]
	v_mul_f32_e32 v4, 0x37800000, v3
	v_cndmask_b32_e32 v3, v3, v4, vcc
	v_cmp_class_f32_e32 vcc, v2, v220
	s_nop 1
	v_cndmask_b32_e32 v2, v3, v2, vcc
	v_div_scale_f32 v3, s[0:1], v2, v2, 1.0
	v_rcp_f32_e32 v4, v3
	s_movk_i32 s0, 0x4000
	v_fma_f32 v5, -v3, v4, 1.0
	v_fmac_f32_e32 v4, v5, v4
	v_div_scale_f32 v5, vcc, 1.0, v2, 1.0
	v_mul_f32_e32 v11, v5, v4
	v_fma_f32 v12, -v3, v11, v5
	v_fmac_f32_e32 v11, v12, v4
	v_fma_f32 v3, -v3, v11, v5
	v_div_fmas_f32 v3, v3, v4, v11
	v_div_fixup_f32 v11, v3, v2, 1.0
	v_mul_f32_e32 v2, v71, v11
	v_mul_f32_e32 v2, v64, v2
	v_add_co_u32_e32 v4, vcc, s0, v0
	v_bfe_u32 v3, v2, 16, 1
	s_nop 0
	v_addc_co_u32_e32 v5, vcc, 0, v1, vcc
	s_movk_i32 s0, 0x5000
	v_add3_u32 v12, v2, v3, s30
	v_add_co_u32_e32 v2, vcc, s0, v0
	s_nop 1
	v_addc_co_u32_e32 v3, vcc, 0, v1, vcc
	global_store_short_d16_hi v[2:3], v12, off offset:-4096
	v_mul_f32_e32 v12, v59, v11
	v_mul_f32_e32 v12, v65, v12
	v_bfe_u32 v13, v12, 16, 1
	v_add3_u32 v12, v12, v13, s30
	global_store_short_d16_hi v[4:5], v12, off offset:64
	v_mul_f32_e32 v12, v43, v11
	v_mul_f32_e32 v12, v66, v12
	v_bfe_u32 v13, v12, 16, 1
	v_mul_f32_e32 v11, v30, v11
	v_add3_u32 v12, v12, v13, s30
	v_mul_f32_e32 v11, v67, v11
	global_store_short_d16_hi v[4:5], v12, off offset:128
	v_bfe_u32 v12, v11, 16, 1
	v_add3_u32 v11, v11, v12, s30
	global_store_short_d16_hi v[4:5], v11, off offset:192
	v_mul_f32_e32 v11, v58, v58
	v_fmac_f32_e32 v11, v70, v70
	v_fmac_f32_e32 v11, v42, v42
	v_fmac_f32_e32 v11, v29, v29
	s_nop 1
	s_waitcnt lgkmcnt(0)
	v_add_f32_dpp v11, v11, v11 quad_perm:[1,0,3,2] row_mask:0xf bank_mask:0xf
	s_nop 1
	s_waitcnt lgkmcnt(0)
	v_add_f32_dpp v11, v11, v11 quad_perm:[2,3,0,1] row_mask:0xf bank_mask:0xf
	s_nop 1
	s_waitcnt lgkmcnt(0)
	v_add_f32_dpp v11, v11, v11 row_half_mirror row_mask:0xf bank_mask:0xf
	s_nop 1
	s_waitcnt lgkmcnt(0)
	v_add_f32_dpp v11, v11, v11 row_mirror row_mask:0xf bank_mask:0xf
	v_mov_b32_e32 v12, v11
	s_waitcnt lgkmcnt(0)
; __device__ __forceinline__ unsigned f2bf(float f) { unsigned u = __builtin_bit_cast(unsigned, f); return (u + 0x7fffu + ((u >> 16) & 1u)) >> 16; }
; __device__ __forceinline__ int crow(int r, int hi) { return (r & 3) + 8 * (r >> 2) + 4 * hi; }
; __device__ __forceinline__ void attn_unit(const bf16* __restrict__ P, bf16* __restrict__ MIXIN, const float* __restrict__ gn, int seq0, int h, int q0, int nt, float kmax0, float kmax1, float slope, float lam, char* lds) {
;     ...
;     for (int r = 0; r < 16; ++r) {
;       float ss = o[0][r] * o[0][r] + o[1][r] * o[1][r] + o[2][r] * o[2][r] + o[3][r] * o[3][r];
;       ss += __shfl_xor(ss, 1); ss += __shfl_xor(ss, 2); ss += __shfl_xor(ss, 4); ss += __shfl_xor(ss, 8); ss += __shfl_xor(ss, 16);
;       const float sc_ = 1.0f / sqrtf(ss * (1.0f / 128.0f) + EPS);
;       const int orow = crow(r, hie);
; #pragma unroll
;       for (int d0 = 0; d0 < 4; ++d0) Ow[(size_t)orow * DM + d0 * 32] = (bf16)f2bf(o[d0][r] * sc_ * g4[d0]);
	s_nop 0
	v_permlane16_swap_b32_e32 v11, v12
	v_add_f32_e32 v11, v11, v12
	v_fmamk_f32 v11, v11, 0x3c000000, v221
	v_cmp_gt_f32_e32 vcc, s26, v11
	v_mul_f32_e32 v12, 0x4f800000, v11
	s_nop 0
	v_cndmask_b32_e32 v11, v11, v12, vcc
	v_sqrt_f32_e32 v12, v11
	s_nop 0
	v_add_u32_e32 v13, -1, v12
	v_fma_f32 v14, -v13, v12, v11
	v_cmp_ge_f32_e64 s[0:1], 0, v14
	v_add_u32_e32 v14, 1, v12
	s_nop 0
	v_cndmask_b32_e64 v13, v12, v13, s[0:1]
	v_fma_f32 v12, -v14, v12, v11
	v_cmp_lt_f32_e64 s[0:1], 0, v12
	s_nop 1
	v_cndmask_b32_e64 v12, v13, v14, s[0:1]
	v_mul_f32_e32 v13, 0x37800000, v12
	v_cndmask_b32_e32 v12, v12, v13, vcc
	v_cmp_class_f32_e32 vcc, v11, v220
	s_nop 1
	v_cndmask_b32_e32 v11, v12, v11, vcc
	v_div_scale_f32 v12, s[0:1], v11, v11, 1.0
	v_rcp_f32_e32 v13, v12
	s_nop 0
	v_fma_f32 v14, -v12, v13, 1.0
	v_fmac_f32_e32 v13, v14, v13
	v_div_scale_f32 v14, vcc, 1.0, v11, 1.0
	v_mul_f32_e32 v15, v14, v13
	v_fma_f32 v30, -v12, v15, v14
	v_fmac_f32_e32 v15, v30, v13
	v_fma_f32 v12, -v12, v15, v14
	v_div_fmas_f32 v12, v12, v13, v15
	v_div_fixup_f32 v11, v12, v11, 1.0
	v_mul_f32_e32 v12, v70, v11
	v_mul_f32_e32 v12, v64, v12
	v_bfe_u32 v13, v12, 16, 1
	v_add3_u32 v12, v12, v13, s30
	global_store_short_d16_hi v[4:5], v12, off offset:2048
	v_mul_f32_e32 v12, v58, v11
	v_mul_f32_e32 v12, v65, v12
	v_bfe_u32 v13, v12, 16, 1
	v_add3_u32 v12, v12, v13, s30
	global_store_short_d16_hi v[4:5], v12, off offset:2112
	v_mul_f32_e32 v12, v42, v11
	v_mul_f32_e32 v12, v66, v12
	v_bfe_u32 v13, v12, 16, 1
	v_mul_f32_e32 v11, v29, v11
	v_add3_u32 v12, v12, v13, s30
	v_mul_f32_e32 v11, v67, v11
	global_store_short_d16_hi v[4:5], v12, off offset:2176
	v_bfe_u32 v12, v11, 16, 1
	v_add3_u32 v11, v11, v12, s30
	global_store_short_d16_hi v[4:5], v11, off offset:2240
	v_mul_f32_e32 v4, v57, v57
	v_fmac_f32_e32 v4, v69, v69
	v_fmac_f32_e32 v4, v41, v41
	v_fmac_f32_e32 v4, v28, v28
	s_nop 1
	s_waitcnt lgkmcnt(0)
	v_add_f32_dpp v4, v4, v4 quad_perm:[1,0,3,2] row_mask:0xf bank_mask:0xf
	s_nop 1
	s_waitcnt lgkmcnt(0)
	v_add_f32_dpp v4, v4, v4 quad_perm:[2,3,0,1] row_mask:0xf bank_mask:0xf
	s_nop 1
	s_waitcnt lgkmcnt(0)
	v_add_f32_dpp v4, v4, v4 row_half_mirror row_mask:0xf bank_mask:0xf
	s_nop 1
	s_waitcnt lgkmcnt(0)
	v_add_f32_dpp v4, v4, v4 row_mirror row_mask:0xf bank_mask:0xf
	v_mov_b32_e32 v5, v4
	s_waitcnt lgkmcnt(0)
	s_nop 0
	v_permlane16_swap_b32_e32 v4, v5
	v_add_f32_e32 v4, v4, v5
	v_fmamk_f32 v4, v4, 0x3c000000, v221
	v_cmp_gt_f32_e32 vcc, s26, v4
	v_mul_f32_e32 v5, 0x4f800000, v4
	s_nop 0
	v_cndmask_b32_e32 v4, v4, v5, vcc
	v_sqrt_f32_e32 v5, v4
	s_nop 0
	v_add_u32_e32 v11, -1, v5
	v_fma_f32 v12, -v11, v5, v4
	v_cmp_ge_f32_e64 s[0:1], 0, v12
	v_add_u32_e32 v12, 1, v5
	s_nop 0
	v_cndmask_b32_e64 v11, v5, v11, s[0:1]
	v_fma_f32 v5, -v12, v5, v4
	v_cmp_lt_f32_e64 s[0:1], 0, v5
	s_nop 1
	v_cndmask_b32_e64 v5, v11, v12, s[0:1]
	v_mul_f32_e32 v11, 0x37800000, v5
	v_cndmask_b32_e32 v5, v5, v11, vcc
	v_cmp_class_f32_e32 vcc, v4, v220
	s_nop 1
	v_cndmask_b32_e32 v4, v5, v4, vcc
	v_div_scale_f32 v5, s[0:1], v4, v4, 1.0
	v_rcp_f32_e32 v11, v5
	s_nop 0
	v_fma_f32 v12, -v5, v11, 1.0
	v_fmac_f32_e32 v11, v12, v11
	v_div_scale_f32 v12, vcc, 1.0, v4, 1.0
	v_mul_f32_e32 v13, v12, v11
	v_fma_f32 v14, -v5, v13, v12
	v_fmac_f32_e32 v13, v14, v11
	v_fma_f32 v5, -v5, v13, v12
	v_div_fmas_f32 v5, v5, v11, v13
	v_div_fixup_f32 v4, v5, v4, 1.0
	v_mul_f32_e32 v5, v69, v4
	v_mul_f32_e32 v5, v64, v5
	v_bfe_u32 v11, v5, 16, 1
	v_add3_u32 v5, v5, v11, s30
	global_store_short_d16_hi v[2:3], v5, off
	v_mul_f32_e32 v5, v57, v4
	v_mul_f32_e32 v5, v65, v5
	v_bfe_u32 v11, v5, 16, 1
	v_add3_u32 v5, v5, v11, s30
	global_store_short_d16_hi v[2:3], v5, off offset:64
	v_mul_f32_e32 v5, v41, v4
	v_mul_f32_e32 v5, v66, v5
	v_bfe_u32 v11, v5, 16, 1
	v_mul_f32_e32 v4, v28, v4
	v_add3_u32 v5, v5, v11, s30
	v_mul_f32_e32 v4, v67, v4
	global_store_short_d16_hi v[2:3], v5, off offset:128
	v_bfe_u32 v5, v4, 16, 1
	v_add3_u32 v4, v4, v5, s30
	global_store_short_d16_hi v[2:3], v4, off offset:192
	v_mul_f32_e32 v4, v56, v56
	v_fmac_f32_e32 v4, v68, v68
	v_fmac_f32_e32 v4, v40, v40
	v_fmac_f32_e32 v4, v27, v27
	s_nop 1
	s_waitcnt lgkmcnt(0)
	v_add_f32_dpp v4, v4, v4 quad_perm:[1,0,3,2] row_mask:0xf bank_mask:0xf
	s_nop 1
	s_waitcnt lgkmcnt(0)
	v_add_f32_dpp v4, v4, v4 quad_perm:[2,3,0,1] row_mask:0xf bank_mask:0xf
	s_nop 1
	s_waitcnt lgkmcnt(0)
	v_add_f32_dpp v4, v4, v4 row_half_mirror row_mask:0xf bank_mask:0xf
	s_nop 1
	s_waitcnt lgkmcnt(0)
	v_add_f32_dpp v4, v4, v4 row_mirror row_mask:0xf bank_mask:0xf
	v_mov_b32_e32 v5, v4
	s_waitcnt lgkmcnt(0)
	s_nop 0
	v_permlane16_swap_b32_e32 v4, v5
	v_add_f32_e32 v4, v4, v5
	v_fmamk_f32 v4, v4, 0x3c000000, v221
	v_cmp_gt_f32_e32 vcc, s26, v4
	v_mul_f32_e32 v5, 0x4f800000, v4
	s_nop 0
	v_cndmask_b32_e32 v4, v4, v5, vcc
	v_sqrt_f32_e32 v5, v4
	s_nop 0
	v_add_u32_e32 v11, -1, v5
	v_fma_f32 v12, -v11, v5, v4
	v_cmp_ge_f32_e64 s[0:1], 0, v12
	v_add_u32_e32 v12, 1, v5
	s_nop 0
	v_cndmask_b32_e64 v11, v5, v11, s[0:1]
	v_fma_f32 v5, -v12, v5, v4
	v_cmp_lt_f32_e64 s[0:1], 0, v5
	s_nop 1
	v_cndmask_b32_e64 v5, v11, v12, s[0:1]
	v_mul_f32_e32 v11, 0x37800000, v5
	v_cndmask_b32_e32 v5, v5, v11, vcc
	v_cmp_class_f32_e32 vcc, v4, v220
	s_nop 1
	v_cndmask_b32_e32 v4, v5, v4, vcc
	v_div_scale_f32 v5, s[0:1], v4, v4, 1.0
	v_rcp_f32_e32 v11, v5
	s_nop 0
	v_fma_f32 v12, -v5, v11, 1.0
	v_fmac_f32_e32 v11, v12, v11
	v_div_scale_f32 v12, vcc, 1.0, v4, 1.0
	v_mul_f32_e32 v13, v12, v11
	v_fma_f32 v14, -v5, v13, v12
	v_fmac_f32_e32 v13, v14, v11
	v_fma_f32 v5, -v5, v13, v12
	v_div_fmas_f32 v5, v5, v11, v13
	v_div_fixup_f32 v4, v5, v4, 1.0
	v_mul_f32_e32 v5, v68, v4
	v_mul_f32_e32 v5, v64, v5
	v_bfe_u32 v11, v5, 16, 1
	v_add3_u32 v5, v5, v11, s30
	global_store_short_d16_hi v[2:3], v5, off offset:2048
	v_mul_f32_e32 v5, v56, v4
	v_mul_f32_e32 v5, v65, v5
	v_bfe_u32 v11, v5, 16, 1
	v_add3_u32 v5, v5, v11, s30
	global_store_short_d16_hi v[2:3], v5, off offset:2112
	v_mul_f32_e32 v5, v40, v4
	v_mul_f32_e32 v5, v66, v5
	v_bfe_u32 v11, v5, 16, 1
	v_mul_f32_e32 v4, v27, v4
	v_add3_u32 v5, v5, v11, s30
	v_mul_f32_e32 v4, v67, v4
	global_store_short_d16_hi v[2:3], v5, off offset:2176
	v_bfe_u32 v5, v4, 16, 1
	v_add3_u32 v4, v4, v5, s30
	global_store_short_d16_hi v[2:3], v4, off offset:2240
	v_mul_f32_e32 v2, v39, v39
	v_fmac_f32_e32 v2, v55, v55
	v_fmac_f32_e32 v2, v24, v24
	v_fmac_f32_e32 v2, v26, v26
	s_nop 1
	s_waitcnt lgkmcnt(0)
; __device__ __forceinline__ unsigned f2bf(float f) { unsigned u = __builtin_bit_cast(unsigned, f); return (u + 0x7fffu + ((u >> 16) & 1u)) >> 16; }
; __device__ __forceinline__ int crow(int r, int hi) { return (r & 3) + 8 * (r >> 2) + 4 * hi; }
; __device__ __forceinline__ void attn_unit(const bf16* __restrict__ P, bf16* __restrict__ MIXIN, const float* __restrict__ gn, int seq0, int h, int q0, int nt, float kmax0, float kmax1, float slope, float lam, char* lds) {
;     ...
;     for (int r = 0; r < 16; ++r) {
;       float ss = o[0][r] * o[0][r] + o[1][r] * o[1][r] + o[2][r] * o[2][r] + o[3][r] * o[3][r];
;       ss += __shfl_xor(ss, 1); ss += __shfl_xor(ss, 2); ss += __shfl_xor(ss, 4); ss += __shfl_xor(ss, 8); ss += __shfl_xor(ss, 16);
;       const float sc_ = 1.0f / sqrtf(ss * (1.0f / 128.0f) + EPS);
;       const int orow = crow(r, hie);
; #pragma unroll
;       for (int d0 = 0; d0 < 4; ++d0) Ow[(size_t)orow * DM + d0 * 32] = (bf16)f2bf(o[d0][r] * sc_ * g4[d0]);
	v_add_f32_dpp v2, v2, v2 quad_perm:[1,0,3,2] row_mask:0xf bank_mask:0xf
	s_nop 1
	s_waitcnt lgkmcnt(0)
	v_add_f32_dpp v2, v2, v2 quad_perm:[2,3,0,1] row_mask:0xf bank_mask:0xf
	s_nop 1
	s_waitcnt lgkmcnt(0)
	v_add_f32_dpp v2, v2, v2 row_half_mirror row_mask:0xf bank_mask:0xf
	s_nop 1
	s_waitcnt lgkmcnt(0)
	v_add_f32_dpp v2, v2, v2 row_mirror row_mask:0xf bank_mask:0xf
	v_mov_b32_e32 v3, v2
	s_waitcnt lgkmcnt(0)
	s_nop 0
	v_permlane16_swap_b32_e32 v2, v3
	v_add_f32_e32 v2, v2, v3
	v_fmamk_f32 v2, v2, 0x3c000000, v221
	v_cmp_gt_f32_e32 vcc, s26, v2
	v_mul_f32_e32 v3, 0x4f800000, v2
	s_nop 0
	v_cndmask_b32_e32 v2, v2, v3, vcc
	v_sqrt_f32_e32 v3, v2
	s_nop 0
	v_add_u32_e32 v4, -1, v3
	v_fma_f32 v5, -v4, v3, v2
	v_cmp_ge_f32_e64 s[0:1], 0, v5
	v_add_u32_e32 v5, 1, v3
	s_nop 0
	v_cndmask_b32_e64 v4, v3, v4, s[0:1]
	v_fma_f32 v3, -v5, v3, v2
	v_cmp_lt_f32_e64 s[0:1], 0, v3
	s_nop 1
	v_cndmask_b32_e64 v3, v4, v5, s[0:1]
	v_mul_f32_e32 v4, 0x37800000, v3
	v_cndmask_b32_e32 v3, v3, v4, vcc
	v_cmp_class_f32_e32 vcc, v2, v220
	s_nop 1
	v_cndmask_b32_e32 v2, v3, v2, vcc
	v_div_scale_f32 v3, s[0:1], v2, v2, 1.0
	v_rcp_f32_e32 v4, v3
	s_mov_b32 s0, 0x8000
	v_fma_f32 v5, -v3, v4, 1.0
	v_fmac_f32_e32 v4, v5, v4
	v_div_scale_f32 v5, vcc, 1.0, v2, 1.0
	v_mul_f32_e32 v11, v5, v4
	v_fma_f32 v12, -v3, v11, v5
	v_fmac_f32_e32 v11, v12, v4
	v_fma_f32 v3, -v3, v11, v5
	v_div_fmas_f32 v3, v3, v4, v11
	v_div_fixup_f32 v11, v3, v2, 1.0
	v_mul_f32_e32 v2, v55, v11
	v_mul_f32_e32 v2, v64, v2
	v_add_co_u32_e32 v4, vcc, s0, v0
	v_bfe_u32 v3, v2, 16, 1
	s_nop 0
	v_addc_co_u32_e32 v5, vcc, 0, v1, vcc
	s_mov_b32 s0, 0x9000
	v_add3_u32 v12, v2, v3, s30
	v_add_co_u32_e32 v2, vcc, s0, v0
	s_nop 1
	v_addc_co_u32_e32 v3, vcc, 0, v1, vcc
	global_store_short_d16_hi v[2:3], v12, off offset:-4096
	v_mul_f32_e32 v12, v39, v11
	v_mul_f32_e32 v12, v65, v12
	v_bfe_u32 v13, v12, 16, 1
	v_add3_u32 v12, v12, v13, s30
	global_store_short_d16_hi v[4:5], v12, off offset:64
	v_mul_f32_e32 v12, v24, v11
	v_mul_f32_e32 v12, v66, v12
	v_bfe_u32 v13, v12, 16, 1
	v_mul_f32_e32 v11, v26, v11
	v_add3_u32 v12, v12, v13, s30
	v_mul_f32_e32 v11, v67, v11
	global_store_short_d16_hi v[4:5], v12, off offset:128
	v_bfe_u32 v12, v11, 16, 1
	v_add3_u32 v11, v11, v12, s30
	global_store_short_d16_hi v[4:5], v11, off offset:192
	v_mul_f32_e32 v11, v38, v38
	v_fmac_f32_e32 v11, v54, v54
	v_fmac_f32_e32 v11, v23, v23
	v_fmac_f32_e32 v11, v25, v25
	s_nop 1
	s_waitcnt lgkmcnt(0)
	v_add_f32_dpp v11, v11, v11 quad_perm:[1,0,3,2] row_mask:0xf bank_mask:0xf
	s_nop 1
	s_waitcnt lgkmcnt(0)
	v_add_f32_dpp v11, v11, v11 quad_perm:[2,3,0,1] row_mask:0xf bank_mask:0xf
	s_nop 1
	s_waitcnt lgkmcnt(0)
	v_add_f32_dpp v11, v11, v11 row_half_mirror row_mask:0xf bank_mask:0xf
	s_nop 1
	s_waitcnt lgkmcnt(0)
	v_add_f32_dpp v11, v11, v11 row_mirror row_mask:0xf bank_mask:0xf
	v_mov_b32_e32 v12, v11
	s_waitcnt lgkmcnt(0)
	s_nop 0
	v_permlane16_swap_b32_e32 v11, v12
	v_add_f32_e32 v11, v11, v12
	v_fmamk_f32 v11, v11, 0x3c000000, v221
	v_cmp_gt_f32_e32 vcc, s26, v11
	v_mul_f32_e32 v12, 0x4f800000, v11
	s_nop 0
	v_cndmask_b32_e32 v11, v11, v12, vcc
	v_sqrt_f32_e32 v12, v11
	s_nop 0
	v_add_u32_e32 v13, -1, v12
	v_fma_f32 v14, -v13, v12, v11
	v_cmp_ge_f32_e64 s[0:1], 0, v14
	v_add_u32_e32 v14, 1, v12
	s_nop 0
	v_cndmask_b32_e64 v13, v12, v13, s[0:1]
	v_fma_f32 v12, -v14, v12, v11
	v_cmp_lt_f32_e64 s[0:1], 0, v12
	s_nop 1
	v_cndmask_b32_e64 v12, v13, v14, s[0:1]
	v_mul_f32_e32 v13, 0x37800000, v12
	v_cndmask_b32_e32 v12, v12, v13, vcc
	v_cmp_class_f32_e32 vcc, v11, v220
	s_nop 1
	v_cndmask_b32_e32 v11, v12, v11, vcc
	v_div_scale_f32 v12, s[0:1], v11, v11, 1.0
	v_rcp_f32_e32 v13, v12
	s_nop 0
	v_fma_f32 v14, -v12, v13, 1.0
	v_fmac_f32_e32 v13, v14, v13
	v_div_scale_f32 v14, vcc, 1.0, v11, 1.0
	v_mul_f32_e32 v15, v14, v13
	v_fma_f32 v24, -v12, v15, v14
	v_fmac_f32_e32 v15, v24, v13
	v_fma_f32 v12, -v12, v15, v14
	v_div_fmas_f32 v12, v12, v13, v15
	v_div_fixup_f32 v11, v12, v11, 1.0
	v_mul_f32_e32 v12, v54, v11
	v_mul_f32_e32 v12, v64, v12
	v_bfe_u32 v13, v12, 16, 1
	v_add3_u32 v12, v12, v13, s30
	global_store_short_d16_hi v[4:5], v12, off offset:2048
	v_mul_f32_e32 v12, v38, v11
	v_mul_f32_e32 v12, v65, v12
	v_bfe_u32 v13, v12, 16, 1
	v_add3_u32 v12, v12, v13, s30
	global_store_short_d16_hi v[4:5], v12, off offset:2112
	v_mul_f32_e32 v12, v23, v11
	v_mul_f32_e32 v12, v66, v12
	v_bfe_u32 v13, v12, 16, 1
	v_mul_f32_e32 v11, v25, v11
	v_add3_u32 v12, v12, v13, s30
	v_mul_f32_e32 v11, v67, v11
	global_store_short_d16_hi v[4:5], v12, off offset:2176
	v_bfe_u32 v12, v11, 16, 1
	v_add3_u32 v11, v11, v12, s30
	global_store_short_d16_hi v[4:5], v11, off offset:2240
	v_mul_f32_e32 v4, v37, v37
	v_fmac_f32_e32 v4, v53, v53
	v_fmac_f32_e32 v4, v21, v21
	v_fmac_f32_e32 v4, v22, v22
	s_nop 1
	s_waitcnt lgkmcnt(0)
	v_add_f32_dpp v4, v4, v4 quad_perm:[1,0,3,2] row_mask:0xf bank_mask:0xf
	s_nop 1
	s_waitcnt lgkmcnt(0)
	v_add_f32_dpp v4, v4, v4 quad_perm:[2,3,0,1] row_mask:0xf bank_mask:0xf
	s_nop 1
	s_waitcnt lgkmcnt(0)
	v_add_f32_dpp v4, v4, v4 row_half_mirror row_mask:0xf bank_mask:0xf
	s_nop 1
	s_waitcnt lgkmcnt(0)
	v_add_f32_dpp v4, v4, v4 row_mirror row_mask:0xf bank_mask:0xf
	v_mov_b32_e32 v5, v4
	s_waitcnt lgkmcnt(0)
; __device__ __forceinline__ unsigned f2bf(float f) { unsigned u = __builtin_bit_cast(unsigned, f); return (u + 0x7fffu + ((u >> 16) & 1u)) >> 16; }
; __device__ __forceinline__ int crow(int r, int hi) { return (r & 3) + 8 * (r >> 2) + 4 * hi; }
; __device__ __forceinline__ void attn_unit(const bf16* __restrict__ P, bf16* __restrict__ MIXIN, const float* __restrict__ gn, int seq0, int h, int q0, int nt, float kmax0, float kmax1, float slope, float lam, char* lds) {
;     ...
;     for (int r = 0; r < 16; ++r) {
;       float ss = o[0][r] * o[0][r] + o[1][r] * o[1][r] + o[2][r] * o[2][r] + o[3][r] * o[3][r];
;       ss += __shfl_xor(ss, 1); ss += __shfl_xor(ss, 2); ss += __shfl_xor(ss, 4); ss += __shfl_xor(ss, 8); ss += __shfl_xor(ss, 16);
;       const float sc_ = 1.0f / sqrtf(ss * (1.0f / 128.0f) + EPS);
;       const int orow = crow(r, hie);
; #pragma unroll
;       for (int d0 = 0; d0 < 4; ++d0) Ow[(size_t)orow * DM + d0 * 32] = (bf16)f2bf(o[d0][r] * sc_ * g4[d0]);
	s_nop 0
	v_permlane16_swap_b32_e32 v4, v5
	v_add_f32_e32 v4, v4, v5
	v_fmamk_f32 v4, v4, 0x3c000000, v221
	v_cmp_gt_f32_e32 vcc, s26, v4
	v_mul_f32_e32 v5, 0x4f800000, v4
	s_nop 0
	v_cndmask_b32_e32 v4, v4, v5, vcc
	v_sqrt_f32_e32 v5, v4
	s_nop 0
	v_add_u32_e32 v11, -1, v5
	v_fma_f32 v12, -v11, v5, v4
	v_cmp_ge_f32_e64 s[0:1], 0, v12
	v_add_u32_e32 v12, 1, v5
	s_nop 0
	v_cndmask_b32_e64 v11, v5, v11, s[0:1]
	v_fma_f32 v5, -v12, v5, v4
	v_cmp_lt_f32_e64 s[0:1], 0, v5
	s_nop 1
	v_cndmask_b32_e64 v5, v11, v12, s[0:1]
	v_mul_f32_e32 v11, 0x37800000, v5
	v_cndmask_b32_e32 v5, v5, v11, vcc
	v_cmp_class_f32_e32 vcc, v4, v220
	s_nop 1
	v_cndmask_b32_e32 v4, v5, v4, vcc
	v_div_scale_f32 v5, s[0:1], v4, v4, 1.0
	v_rcp_f32_e32 v11, v5
	s_nop 0
	v_fma_f32 v12, -v5, v11, 1.0
	v_fmac_f32_e32 v11, v12, v11
	v_div_scale_f32 v12, vcc, 1.0, v4, 1.0
	v_mul_f32_e32 v13, v12, v11
	v_fma_f32 v14, -v5, v13, v12
	v_fmac_f32_e32 v13, v14, v11
	v_fma_f32 v5, -v5, v13, v12
	v_div_fmas_f32 v5, v5, v11, v13
	v_div_fixup_f32 v4, v5, v4, 1.0
	v_mul_f32_e32 v5, v53, v4
	v_mul_f32_e32 v5, v64, v5
	v_bfe_u32 v11, v5, 16, 1
	v_add3_u32 v5, v5, v11, s30
	global_store_short_d16_hi v[2:3], v5, off
	v_mul_f32_e32 v5, v37, v4
	v_mul_f32_e32 v5, v65, v5
	v_bfe_u32 v11, v5, 16, 1
	v_add3_u32 v5, v5, v11, s30
	global_store_short_d16_hi v[2:3], v5, off offset:64
	v_mul_f32_e32 v5, v21, v4
	v_mul_f32_e32 v5, v66, v5
	v_bfe_u32 v11, v5, 16, 1
	v_mul_f32_e32 v4, v22, v4
	v_add3_u32 v5, v5, v11, s30
	v_mul_f32_e32 v4, v67, v4
	global_store_short_d16_hi v[2:3], v5, off offset:128
	v_bfe_u32 v5, v4, 16, 1
	v_add3_u32 v4, v4, v5, s30
	global_store_short_d16_hi v[2:3], v4, off offset:192
	v_mul_f32_e32 v4, v36, v36
	v_fmac_f32_e32 v4, v52, v52
	v_fmac_f32_e32 v4, v20, v20
	v_fmac_f32_e32 v4, v10, v10
	s_nop 1
	s_waitcnt lgkmcnt(0)
	v_add_f32_dpp v4, v4, v4 quad_perm:[1,0,3,2] row_mask:0xf bank_mask:0xf
	s_nop 1
	s_waitcnt lgkmcnt(0)
	v_add_f32_dpp v4, v4, v4 quad_perm:[2,3,0,1] row_mask:0xf bank_mask:0xf
	s_nop 1
	s_waitcnt lgkmcnt(0)
	v_add_f32_dpp v4, v4, v4 row_half_mirror row_mask:0xf bank_mask:0xf
	s_nop 1
	s_waitcnt lgkmcnt(0)
	v_add_f32_dpp v4, v4, v4 row_mirror row_mask:0xf bank_mask:0xf
	v_mov_b32_e32 v5, v4
	s_waitcnt lgkmcnt(0)
	s_nop 0
	v_permlane16_swap_b32_e32 v4, v5
	v_add_f32_e32 v4, v4, v5
	v_fmamk_f32 v4, v4, 0x3c000000, v221
	v_cmp_gt_f32_e32 vcc, s26, v4
	v_mul_f32_e32 v5, 0x4f800000, v4
	s_nop 0
	v_cndmask_b32_e32 v4, v4, v5, vcc
	v_sqrt_f32_e32 v5, v4
	s_nop 0
	v_add_u32_e32 v11, -1, v5
	v_fma_f32 v12, -v11, v5, v4
	v_cmp_ge_f32_e64 s[0:1], 0, v12
	v_add_u32_e32 v12, 1, v5
	s_nop 0
	v_cndmask_b32_e64 v11, v5, v11, s[0:1]
	v_fma_f32 v5, -v12, v5, v4
	v_cmp_lt_f32_e64 s[0:1], 0, v5
	s_nop 1
	v_cndmask_b32_e64 v5, v11, v12, s[0:1]
	v_mul_f32_e32 v11, 0x37800000, v5
	v_cndmask_b32_e32 v5, v5, v11, vcc
	v_cmp_class_f32_e32 vcc, v4, v220
	s_nop 1
	v_cndmask_b32_e32 v4, v5, v4, vcc
	v_div_scale_f32 v5, s[0:1], v4, v4, 1.0
	v_rcp_f32_e32 v11, v5
	s_nop 0
	v_fma_f32 v12, -v5, v11, 1.0
	v_fmac_f32_e32 v11, v12, v11
	v_div_scale_f32 v12, vcc, 1.0, v4, 1.0
	v_mul_f32_e32 v13, v12, v11
	v_fma_f32 v14, -v5, v13, v12
	v_fmac_f32_e32 v13, v14, v11
	v_fma_f32 v5, -v5, v13, v12
	v_div_fmas_f32 v5, v5, v11, v13
	v_div_fixup_f32 v4, v5, v4, 1.0
	v_mul_f32_e32 v5, v52, v4
	v_mul_f32_e32 v5, v64, v5
	v_bfe_u32 v11, v5, 16, 1
	v_add3_u32 v5, v5, v11, s30
	global_store_short_d16_hi v[2:3], v5, off offset:2048
	v_mul_f32_e32 v5, v36, v4
	v_mul_f32_e32 v5, v65, v5
	v_bfe_u32 v11, v5, 16, 1
	v_add3_u32 v5, v5, v11, s30
	global_store_short_d16_hi v[2:3], v5, off offset:2112
	v_mul_f32_e32 v5, v20, v4
	v_mul_f32_e32 v5, v66, v5
	v_bfe_u32 v11, v5, 16, 1
	v_mul_f32_e32 v4, v10, v4
	v_add3_u32 v5, v5, v11, s30
	v_mul_f32_e32 v4, v67, v4
	global_store_short_d16_hi v[2:3], v5, off offset:2176
	v_bfe_u32 v5, v4, 16, 1
	v_add3_u32 v4, v4, v5, s30
	global_store_short_d16_hi v[2:3], v4, off offset:2240
	v_mul_f32_e32 v2, v35, v35
	v_fmac_f32_e32 v2, v51, v51
	v_fmac_f32_e32 v2, v19, v19
	v_fmac_f32_e32 v2, v9, v9
	s_nop 1
	s_waitcnt lgkmcnt(0)
	v_add_f32_dpp v2, v2, v2 quad_perm:[1,0,3,2] row_mask:0xf bank_mask:0xf
	s_nop 1
	s_waitcnt lgkmcnt(0)
	v_add_f32_dpp v2, v2, v2 quad_perm:[2,3,0,1] row_mask:0xf bank_mask:0xf
	s_nop 1
	s_waitcnt lgkmcnt(0)
	v_add_f32_dpp v2, v2, v2 row_half_mirror row_mask:0xf bank_mask:0xf
	s_nop 1
	s_waitcnt lgkmcnt(0)
	v_add_f32_dpp v2, v2, v2 row_mirror row_mask:0xf bank_mask:0xf
	v_mov_b32_e32 v3, v2
	s_waitcnt lgkmcnt(0)
	s_nop 0
	v_permlane16_swap_b32_e32 v2, v3
	v_add_f32_e32 v2, v2, v3
	v_fmamk_f32 v2, v2, 0x3c000000, v221
	v_cmp_gt_f32_e32 vcc, s26, v2
	v_mul_f32_e32 v3, 0x4f800000, v2
	s_nop 0
	v_cndmask_b32_e32 v2, v2, v3, vcc
	v_sqrt_f32_e32 v3, v2
	s_nop 0
	v_add_u32_e32 v4, -1, v3
	v_fma_f32 v5, -v4, v3, v2
	v_cmp_ge_f32_e64 s[0:1], 0, v5
	v_add_u32_e32 v5, 1, v3
	s_nop 0
	v_cndmask_b32_e64 v4, v3, v4, s[0:1]
	v_fma_f32 v3, -v5, v3, v2
	v_cmp_lt_f32_e64 s[0:1], 0, v3
	s_nop 1
	v_cndmask_b32_e64 v3, v4, v5, s[0:1]
	v_mul_f32_e32 v4, 0x37800000, v3
	v_cndmask_b32_e32 v3, v3, v4, vcc
	v_cmp_class_f32_e32 vcc, v2, v220
	s_nop 1
	v_cndmask_b32_e32 v2, v3, v2, vcc
	v_div_scale_f32 v3, s[0:1], v2, v2, 1.0
	v_rcp_f32_e32 v4, v3
	s_mov_b32 s0, 0xc000
	v_fma_f32 v5, -v3, v4, 1.0
	v_fmac_f32_e32 v4, v5, v4
	v_div_scale_f32 v5, vcc, 1.0, v2, 1.0
	v_mul_f32_e32 v10, v5, v4
	v_fma_f32 v11, -v3, v10, v5
	v_fmac_f32_e32 v10, v11, v4
	v_fma_f32 v3, -v3, v10, v5
	v_div_fmas_f32 v3, v3, v4, v10
	v_div_fixup_f32 v4, v3, v2, 1.0
	v_mul_f32_e32 v2, v51, v4
	v_mul_f32_e32 v2, v64, v2
	v_bfe_u32 v3, v2, 16, 1
	v_add3_u32 v5, v2, v3, s30
	v_add_co_u32_e32 v2, vcc, s0, v0
	s_mov_b32 s0, 0xd000
	s_nop 0
	v_addc_co_u32_e32 v3, vcc, 0, v1, vcc
	v_add_co_u32_e32 v0, vcc, s0, v0
	s_nop 1
	v_addc_co_u32_e32 v1, vcc, 0, v1, vcc
	global_store_short_d16_hi v[0:1], v5, off offset:-4096
	v_mul_f32_e32 v5, v35, v4
	v_mul_f32_e32 v5, v65, v5
	v_bfe_u32 v10, v5, 16, 1
	v_add3_u32 v5, v5, v10, s30
	global_store_short_d16_hi v[2:3], v5, off offset:64
	v_mul_f32_e32 v5, v19, v4
	v_mul_f32_e32 v5, v66, v5
	v_bfe_u32 v10, v5, 16, 1
	v_mul_f32_e32 v4, v9, v4
	v_add3_u32 v5, v5, v10, s30
	v_mul_f32_e32 v4, v67, v4
	global_store_short_d16_hi v[2:3], v5, off offset:128
	v_bfe_u32 v5, v4, 16, 1
	v_add3_u32 v4, v4, v5, s30
	global_store_short_d16_hi v[2:3], v4, off offset:192
	v_mul_f32_e32 v4, v34, v34
	v_fmac_f32_e32 v4, v50, v50
	v_fmac_f32_e32 v4, v18, v18
	v_fmac_f32_e32 v4, v8, v8
	s_nop 1
	s_waitcnt lgkmcnt(0)
; __device__ __forceinline__ unsigned f2bf(float f) { unsigned u = __builtin_bit_cast(unsigned, f); return (u + 0x7fffu + ((u >> 16) & 1u)) >> 16; }
; __device__ __forceinline__ int crow(int r, int hi) { return (r & 3) + 8 * (r >> 2) + 4 * hi; }
; __device__ __forceinline__ void attn_unit(const bf16* __restrict__ P, bf16* __restrict__ MIXIN, const float* __restrict__ gn, int seq0, int h, int q0, int nt, float kmax0, float kmax1, float slope, float lam, char* lds) {
;     ...
;     for (int r = 0; r < 16; ++r) {
;       float ss = o[0][r] * o[0][r] + o[1][r] * o[1][r] + o[2][r] * o[2][r] + o[3][r] * o[3][r];
;       ss += __shfl_xor(ss, 1); ss += __shfl_xor(ss, 2); ss += __shfl_xor(ss, 4); ss += __shfl_xor(ss, 8); ss += __shfl_xor(ss, 16);
;       const float sc_ = 1.0f / sqrtf(ss * (1.0f / 128.0f) + EPS);
;       const int orow = crow(r, hie);
; #pragma unroll
;       for (int d0 = 0; d0 < 4; ++d0) Ow[(size_t)orow * DM + d0 * 32] = (bf16)f2bf(o[d0][r] * sc_ * g4[d0]);
;     }
;   }
;   __syncthreads();
	v_add_f32_dpp v4, v4, v4 quad_perm:[1,0,3,2] row_mask:0xf bank_mask:0xf
	s_nop 1
	s_waitcnt lgkmcnt(0)
	v_add_f32_dpp v4, v4, v4 quad_perm:[2,3,0,1] row_mask:0xf bank_mask:0xf
	s_nop 1
	s_waitcnt lgkmcnt(0)
	v_add_f32_dpp v4, v4, v4 row_half_mirror row_mask:0xf bank_mask:0xf
	s_nop 1
	s_waitcnt lgkmcnt(0)
	v_add_f32_dpp v4, v4, v4 row_mirror row_mask:0xf bank_mask:0xf
	v_mov_b32_e32 v5, v4
	s_waitcnt lgkmcnt(0)
	s_nop 0
	v_permlane16_swap_b32_e32 v4, v5
	v_add_f32_e32 v4, v4, v5
	v_fmamk_f32 v4, v4, 0x3c000000, v221
	v_cmp_gt_f32_e32 vcc, s26, v4
	v_mul_f32_e32 v5, 0x4f800000, v4
	s_nop 0
	v_cndmask_b32_e32 v4, v4, v5, vcc
	v_sqrt_f32_e32 v5, v4
	s_nop 0
	v_add_u32_e32 v9, -1, v5
	v_fma_f32 v10, -v9, v5, v4
	v_cmp_ge_f32_e64 s[0:1], 0, v10
	v_add_u32_e32 v10, 1, v5
	s_nop 0
	v_cndmask_b32_e64 v9, v5, v9, s[0:1]
	v_fma_f32 v5, -v10, v5, v4
	v_cmp_lt_f32_e64 s[0:1], 0, v5
	s_nop 1
	v_cndmask_b32_e64 v5, v9, v10, s[0:1]
	v_mul_f32_e32 v9, 0x37800000, v5
	v_cndmask_b32_e32 v5, v5, v9, vcc
	v_cmp_class_f32_e32 vcc, v4, v220
	s_nop 1
	v_cndmask_b32_e32 v4, v5, v4, vcc
	v_div_scale_f32 v5, s[0:1], v4, v4, 1.0
	v_rcp_f32_e32 v9, v5
	s_nop 0
	v_fma_f32 v10, -v5, v9, 1.0
	v_fmac_f32_e32 v9, v10, v9
	v_div_scale_f32 v10, vcc, 1.0, v4, 1.0
	v_mul_f32_e32 v11, v10, v9
	v_fma_f32 v12, -v5, v11, v10
	v_fmac_f32_e32 v11, v12, v9
	v_fma_f32 v5, -v5, v11, v10
	v_div_fmas_f32 v5, v5, v9, v11
	v_div_fixup_f32 v4, v5, v4, 1.0
	v_mul_f32_e32 v5, v50, v4
	v_mul_f32_e32 v5, v64, v5
	v_bfe_u32 v9, v5, 16, 1
	v_add3_u32 v5, v5, v9, s30
	global_store_short_d16_hi v[2:3], v5, off offset:2048
	v_mul_f32_e32 v5, v34, v4
	v_mul_f32_e32 v5, v65, v5
	v_bfe_u32 v9, v5, 16, 1
	v_add3_u32 v5, v5, v9, s30
	global_store_short_d16_hi v[2:3], v5, off offset:2112
	v_mul_f32_e32 v5, v18, v4
	v_mul_f32_e32 v5, v66, v5
	v_bfe_u32 v9, v5, 16, 1
	v_mul_f32_e32 v4, v8, v4
	v_add3_u32 v5, v5, v9, s30
	v_mul_f32_e32 v4, v67, v4
	global_store_short_d16_hi v[2:3], v5, off offset:2176
	v_bfe_u32 v5, v4, 16, 1
	v_add3_u32 v4, v4, v5, s30
	global_store_short_d16_hi v[2:3], v4, off offset:2240
	v_mul_f32_e32 v2, v33, v33
	v_fmac_f32_e32 v2, v49, v49
	v_fmac_f32_e32 v2, v17, v17
	v_fmac_f32_e32 v2, v7, v7
	s_nop 1
	s_waitcnt lgkmcnt(0)
	v_add_f32_dpp v2, v2, v2 quad_perm:[1,0,3,2] row_mask:0xf bank_mask:0xf
	s_nop 1
	s_waitcnt lgkmcnt(0)
	v_add_f32_dpp v2, v2, v2 quad_perm:[2,3,0,1] row_mask:0xf bank_mask:0xf
	s_nop 1
	s_waitcnt lgkmcnt(0)
	v_add_f32_dpp v2, v2, v2 row_half_mirror row_mask:0xf bank_mask:0xf
	s_nop 1
	s_waitcnt lgkmcnt(0)
	v_add_f32_dpp v2, v2, v2 row_mirror row_mask:0xf bank_mask:0xf
	v_mov_b32_e32 v3, v2
	s_waitcnt lgkmcnt(0)
	s_nop 0
	v_permlane16_swap_b32_e32 v2, v3
	v_add_f32_e32 v2, v2, v3
	v_fmamk_f32 v2, v2, 0x3c000000, v221
	v_cmp_gt_f32_e32 vcc, s26, v2
	v_mul_f32_e32 v3, 0x4f800000, v2
	s_nop 0
	v_cndmask_b32_e32 v2, v2, v3, vcc
	v_sqrt_f32_e32 v3, v2
	s_nop 0
	v_add_u32_e32 v4, -1, v3
	v_fma_f32 v5, -v4, v3, v2
	v_cmp_ge_f32_e64 s[0:1], 0, v5
	v_add_u32_e32 v5, 1, v3
	s_nop 0
	v_cndmask_b32_e64 v4, v3, v4, s[0:1]
	v_fma_f32 v3, -v5, v3, v2
	v_cmp_lt_f32_e64 s[0:1], 0, v3
	s_nop 1
	v_cndmask_b32_e64 v3, v4, v5, s[0:1]
	v_mul_f32_e32 v4, 0x37800000, v3
	v_cndmask_b32_e32 v3, v3, v4, vcc
	v_cmp_class_f32_e32 vcc, v2, v220
	s_nop 1
	v_cndmask_b32_e32 v2, v3, v2, vcc
	v_div_scale_f32 v3, s[0:1], v2, v2, 1.0
	v_rcp_f32_e32 v4, v3
	s_nop 0
	v_fma_f32 v5, -v3, v4, 1.0
	v_fmac_f32_e32 v4, v5, v4
	v_div_scale_f32 v5, vcc, 1.0, v2, 1.0
	v_mul_f32_e32 v8, v5, v4
	v_fma_f32 v9, -v3, v8, v5
	v_fmac_f32_e32 v8, v9, v4
	v_fma_f32 v3, -v3, v8, v5
	v_div_fmas_f32 v3, v3, v4, v8
	v_div_fixup_f32 v2, v3, v2, 1.0
	v_mul_f32_e32 v3, v49, v2
	v_mul_f32_e32 v3, v64, v3
	v_bfe_u32 v4, v3, 16, 1
	v_add3_u32 v3, v3, v4, s30
	global_store_short_d16_hi v[0:1], v3, off
	v_mul_f32_e32 v3, v33, v2
	v_mul_f32_e32 v3, v65, v3
	v_bfe_u32 v4, v3, 16, 1
	v_add3_u32 v3, v3, v4, s30
	global_store_short_d16_hi v[0:1], v3, off offset:64
	v_mul_f32_e32 v3, v17, v2
	v_mul_f32_e32 v3, v66, v3
	v_bfe_u32 v4, v3, 16, 1
	v_mul_f32_e32 v2, v7, v2
	v_add3_u32 v3, v3, v4, s30
	v_mul_f32_e32 v2, v67, v2
	global_store_short_d16_hi v[0:1], v3, off offset:128
	v_bfe_u32 v3, v2, 16, 1
	v_add3_u32 v2, v2, v3, s30
	global_store_short_d16_hi v[0:1], v2, off offset:192
	v_mul_f32_e32 v2, v32, v32
	v_fmac_f32_e32 v2, v48, v48
	v_fmac_f32_e32 v2, v16, v16
	v_fmac_f32_e32 v2, v6, v6
	s_nop 1
	s_waitcnt lgkmcnt(0)
	v_add_f32_dpp v2, v2, v2 quad_perm:[1,0,3,2] row_mask:0xf bank_mask:0xf
	s_nop 1
	s_waitcnt lgkmcnt(0)
	v_add_f32_dpp v2, v2, v2 quad_perm:[2,3,0,1] row_mask:0xf bank_mask:0xf
	s_nop 1
	s_waitcnt lgkmcnt(0)
	v_add_f32_dpp v2, v2, v2 row_half_mirror row_mask:0xf bank_mask:0xf
	s_nop 1
	s_waitcnt lgkmcnt(0)
	v_add_f32_dpp v2, v2, v2 row_mirror row_mask:0xf bank_mask:0xf
	v_mov_b32_e32 v3, v2
	s_waitcnt lgkmcnt(0)
	s_nop 0
	v_permlane16_swap_b32_e32 v2, v3
	v_add_f32_e32 v2, v2, v3
	v_fmamk_f32 v2, v2, 0x3c000000, v221
	v_cmp_gt_f32_e32 vcc, s26, v2
	v_mul_f32_e32 v3, 0x4f800000, v2
	s_nop 0
	v_cndmask_b32_e32 v2, v2, v3, vcc
	v_sqrt_f32_e32 v3, v2
	s_nop 0
	v_add_u32_e32 v4, -1, v3
	v_fma_f32 v5, -v4, v3, v2
	v_cmp_ge_f32_e64 s[0:1], 0, v5
	v_add_u32_e32 v5, 1, v3
	s_nop 0
	v_cndmask_b32_e64 v4, v3, v4, s[0:1]
	v_fma_f32 v3, -v5, v3, v2
	v_cmp_lt_f32_e64 s[0:1], 0, v3
	s_nop 1
	v_cndmask_b32_e64 v3, v4, v5, s[0:1]
	v_mul_f32_e32 v4, 0x37800000, v3
	v_cndmask_b32_e32 v3, v3, v4, vcc
	v_cmp_class_f32_e32 vcc, v2, v220
	s_nop 1
	v_cndmask_b32_e32 v2, v3, v2, vcc
	v_div_scale_f32 v3, s[0:1], v2, v2, 1.0
	v_rcp_f32_e32 v4, v3
	s_nop 0
	v_fma_f32 v5, -v3, v4, 1.0
	v_fmac_f32_e32 v4, v5, v4
	v_div_scale_f32 v5, vcc, 1.0, v2, 1.0
	v_mul_f32_e32 v7, v5, v4
	v_fma_f32 v8, -v3, v7, v5
	v_fmac_f32_e32 v7, v8, v4
	v_fma_f32 v3, -v3, v7, v5
	v_div_fmas_f32 v3, v3, v4, v7
	v_div_fixup_f32 v2, v3, v2, 1.0
	v_mul_f32_e32 v3, v48, v2
	v_mul_f32_e32 v3, v64, v3
	v_bfe_u32 v4, v3, 16, 1
	v_add3_u32 v3, v3, v4, s30
	global_store_short_d16_hi v[0:1], v3, off offset:2048
	v_mul_f32_e32 v3, v32, v2
	v_mul_f32_e32 v3, v65, v3
	v_bfe_u32 v4, v3, 16, 1
	v_add3_u32 v3, v3, v4, s30
	global_store_short_d16_hi v[0:1], v3, off offset:2112
	v_mul_f32_e32 v3, v16, v2
	v_mul_f32_e32 v3, v66, v3
	v_bfe_u32 v4, v3, 16, 1
	v_mul_f32_e32 v2, v6, v2
	v_add3_u32 v3, v3, v4, s30
	v_mul_f32_e32 v2, v67, v2
	global_store_short_d16_hi v[0:1], v3, off offset:2176
	v_bfe_u32 v3, v2, 16, 1
	v_add3_u32 v2, v2, v3, s30
	global_store_short_d16_hi v[0:1], v2, off offset:2240
	s_branch .LBB0_291
